# P2b reciprocal via v_rcp_f32 (sigmoid and 1/norm) instead of IEEE division sequence
# baseline (speedup 1.0000x reference)
; DI float sigmoidf_(float x) { return 1.f / (1.f + __expf(-x)); }
; __global__ void __launch_bounds__(NTHR, 2) fwd_kernel(Params p) {
;     ...
;     for (int t = bid * 8 + wv; t < T; t += nblk * 8) {
;       const size_t o = (size_t)t * 256 + c;
;       const f32x4 r = sm4(zraw, mu, t, c), k = sm4(zraw, mu, t, 256 + c), v = sm4(zraw, mu, t, 512 + c);
;       f32x4 lo = sm4(zraw, mu, t, 768 + c);
;       f32x4 kk; kk[0] = k[0] * kkw.x; kk[1] = k[1] * kkw.y; kk[2] = k[2] * kkw.z; kk[3] = k[3] * kkw.w;
;       const float ss = reduce16(kk[0] * kk[0] + kk[1] * kk[1] + kk[2] * kk[2] + kk[3] * kk[3]);
;       const float inv = 1.f / fmaxf(sqrtf(ss), 1e-12f);
;       kk *= inv;
;       if ((lane & 15) == 0) invn[(size_t)t * 4 + (lane >> 4)] = inv;
;       if (c < 64) {
; #pragma unroll
;         for (int e = 0; e < 4; ++e) lo[e] = tanhf(lo[e]);
;       } else if (c >= 128) {
; #pragma unroll
;         for (int e = 0; e < 4; ++e) lo[e] = sigmoidf_(lo[e]);
;       }
.LBB0_403:
	s_or_b64 exec, exec, s[26:27]
	s_waitcnt vmcnt(4)
	v_lshlrev_b32_e32 v20, 16, v52
	v_and_b32_e32 v21, 0xffff0000, v52
	v_lshlrev_b32_e32 v50, 16, v53
	v_and_b32_e32 v51, 0xffff0000, v53
	v_lshlrev_b32_e32 v52, 16, v18
	v_and_b32_e32 v53, 0xffff0000, v18
	v_lshlrev_b32_e32 v18, 16, v19
	v_and_b32_e32 v19, 0xffff0000, v19
	v_pk_add_f32 v[52:53], v[52:53], v[20:21] neg_lo:[0,1] neg_hi:[0,1]
	v_pk_add_f32 v[18:19], v[18:19], v[50:51] neg_lo:[0,1] neg_hi:[0,1]
	s_waitcnt vmcnt(3)
	v_pk_fma_f32 v[10:11], v[10:11], v[52:53], v[20:21]
	v_pk_fma_f32 v[12:13], v[18:19], v[12:13], v[50:51]
	global_load_dwordx4 v[18:21], v[26:27], off offset:3072
	v_pk_mul_f32 v[50:51], v[2:3], v[10:11]
	v_pk_mul_f32 v[52:53], v[4:5], v[12:13]
	v_pk_mul_f32 v[58:59], v[50:51], v[50:51]
	v_pk_mul_f32 v[60:61], v[52:53], v[52:53]
	v_add_f32_e32 v0, v58, v59
	v_add_f32_e32 v0, v0, v60
	v_add_f32_e32 v0, v0, v61
	s_mov_b32 s8, 0xf800000
	s_nop 0
	v_add_f32_dpp v0, v0, v0 quad_perm:[1,0,3,2] row_mask:0xf bank_mask:0xf bound_ctrl:1
	s_nop 1
	v_add_f32_dpp v0, v0, v0 quad_perm:[2,3,0,1] row_mask:0xf bank_mask:0xf bound_ctrl:1
	s_nop 1
	v_add_f32_dpp v0, v0, v0 row_half_mirror row_mask:0xf bank_mask:0xf bound_ctrl:1
	s_nop 1
	v_add_f32_dpp v0, v0, v0 row_mirror row_mask:0xf bank_mask:0xf bound_ctrl:1
	v_cmp_gt_f32_e32 vcc, s8, v0
	v_mul_f32_e32 v23, 0x4f800000, v0
	s_nop 0
	v_cndmask_b32_e32 v0, v0, v23, vcc
	v_sqrt_f32_e32 v23, v0
	s_nop 0
	v_add_u32_e32 v58, -1, v23
	v_fma_f32 v59, -v58, v23, v0
	v_cmp_ge_f32_e64 s[8:9], 0, v59
	v_add_u32_e32 v59, 1, v23
	s_nop 0
	v_cndmask_b32_e64 v58, v23, v58, s[8:9]
	v_fma_f32 v23, -v59, v23, v0
	v_cmp_lt_f32_e64 s[8:9], 0, v23
	s_nop 1
	v_cndmask_b32_e64 v23, v58, v59, s[8:9]
	v_mul_f32_e32 v58, 0x37800000, v23
	v_cndmask_b32_e32 v23, v23, v58, vcc
	v_mov_b32_e32 v58, 0x260
	v_cmp_class_f32_e32 vcc, v0, v58
	s_nop 1
	v_cndmask_b32_e32 v0, v23, v0, vcc
	v_max_f32_e32 v0, 0x2b8cbccc, v0
	s_nop 0
	v_rcp_f32_e32 v0, v0
	s_and_saveexec_b64 s[8:9], s[2:3]
	s_cbranch_execz .LBB0_405
	v_lshl_add_u64 v[58:59], s[10:11], 0, v[36:37]
	global_store_dword v[58:59], v0, off
.LBB0_405:
	s_or_b64 exec, exec, s[8:9]
	s_waitcnt vmcnt(1)
	v_lshlrev_b32_e32 v58, 16, v56
	v_and_b32_e32 v59, 0xffff0000, v56
	v_lshlrev_b32_e32 v56, 16, v57
	v_and_b32_e32 v57, 0xffff0000, v57
	v_lshlrev_b32_e32 v60, 16, v54
	v_and_b32_e32 v61, 0xffff0000, v54
	v_lshlrev_b32_e32 v54, 16, v55
	v_and_b32_e32 v55, 0xffff0000, v55
	v_pk_add_f32 v[60:61], v[60:61], v[58:59] neg_lo:[0,1] neg_hi:[0,1]
	v_pk_add_f32 v[54:55], v[54:55], v[56:57] neg_lo:[0,1] neg_hi:[0,1]
	s_waitcnt vmcnt(0)
	v_pk_fma_f32 v[18:19], v[18:19], v[60:61], v[58:59]
	v_pk_fma_f32 v[20:21], v[54:55], v[20:21], v[56:57]
	s_and_saveexec_b64 s[8:9], s[4:5]
	s_xor_b64 s[8:9], exec, s[8:9]
	s_cbranch_execz .LBB0_409
	s_and_saveexec_b64 s[26:27], s[6:7]
	s_cbranch_execz .LBB0_408
	v_mul_f32_e32 v18, 0xbfb8aa3b, v18
	v_mul_f32_e32 v19, 0xbfb8aa3b, v19
	v_exp_f32_e32 v18, v18
	v_exp_f32_e32 v19, v19
	v_mul_f32_e32 v20, 0xbfb8aa3b, v20
	v_mul_f32_e32 v21, 0xbfb8aa3b, v21
	v_exp_f32_e32 v20, v20
	v_pk_add_f32 v[18:19], v[18:19], 1.0 op_sel_hi:[1,0]
	v_exp_f32_e32 v21, v21
	s_nop 0
	v_pk_add_f32 v[20:21], v[20:21], 1.0 op_sel_hi:[1,0]
	v_rcp_f32_e32 v18, v18
	s_nop 0
	v_rcp_f32_e32 v19, v19
	s_nop 0
	v_rcp_f32_e32 v20, v20
	s_nop 0
	v_rcp_f32_e32 v21, v21
